# attention loop tail: packed adds with each v_exp interleaved with an independent VALU op
# baseline (speedup 1.0000x reference)
.LBB0_413:
	v_bitop3_b32 v64, s45, v142, v189 bitop3:0x36
	v_bitop3_b32 v72, s45, v143, v189 bitop3:0x36
	v_bitop3_b32 v80, s44, v142, v189 bitop3:0x36
	v_bitop3_b32 v88, s44, v143, v189 bitop3:0x36
	v_mad_i32_i24 v68, v64, s18, v122
	v_mad_i32_i24 v76, v72, s18, v122
	v_mad_i32_i24 v84, v80, s18, v122
	v_mad_i32_i24 v92, v88, s18, v122
	ds_read_b128 v[64:67], v68 offset:18496
	ds_read_b128 v[68:71], v68 offset:18432
	ds_read_b128 v[72:75], v76 offset:18496
	ds_read_b128 v[76:79], v76 offset:18432
	ds_read_b128 v[80:83], v84 offset:18496
	ds_read_b128 v[84:87], v84 offset:18432
	ds_read_b128 v[88:91], v92 offset:18496
	ds_read_b128 v[92:95], v92 offset:18432
	s_waitcnt lgkmcnt(0)
	v_mfma_f32_16x16x32_bf16 v[92:95], v[92:95], v[56:59], 0
	v_cmp_gt_u32_e64 s[60:61], s97, v160
	v_cmp_gt_u32_e64 s[62:63], s97, v161
	v_cmp_gt_u32_e64 s[64:65], s97, v162
	v_cmp_gt_u32_e64 s[72:73], s97, v163
	v_mfma_f32_16x16x32_bf16 v[108:111], v[88:91], v[60:63], v[92:95]
	s_cmp_lt_i32 s51, s42
	s_cselect_b32 s101, s97, 0
	s_cselect_b64 s[2:3], -1, 0
	s_cmp_lg_u64 s[2:3], 0
	v_mfma_f32_16x16x32_bf16 v[84:87], v[84:87], v[56:59], 0
	s_addc_u32 s44, s51, 0
	v_mov_b32_e32 v154, v96
	v_cmp_gt_u32_e64 s[74:75], s97, v164
	v_cmp_gt_u32_e64 s[92:93], s97, v165
	v_cmp_gt_u32_e64 s[94:95], s97, v166
	v_cmp_gt_u32_e64 s[98:99], s97, v167
	s_lshl_b32 s52, s44, 5
	s_lshr_b32 s45, s51, 2
	v_pk_mul_f32 v[108:109], v[108:109], v[126:127] op_sel_hi:[1,0]
	v_pk_mul_f32 v[110:111], v[110:111], v[126:127] op_sel_hi:[1,0]
	v_pk_fma_f32 v[108:109], v[160:161], v[128:129], v[108:109] op_sel:[0,1,0] op_sel_hi:[1,1,1] neg_lo:[0,1,0] neg_hi:[0,1,0]
	v_pk_fma_f32 v[110:111], v[162:163], v[128:129], v[110:111] op_sel:[0,1,0] op_sel_hi:[1,1,1] neg_lo:[0,1,0] neg_hi:[0,1,0]
	v_mfma_f32_16x16x32_bf16 v[104:107], v[80:83], v[60:63], v[84:87]
	v_cndmask_b32_e64 v108, v144, v108, s[60:61]
	v_cndmask_b32_e64 v109, v144, v109, s[62:63]
	v_cndmask_b32_e64 v110, v144, v110, s[64:65]
	v_cndmask_b32_e64 v111, v144, v111, s[72:73]
	v_mfma_f32_16x16x32_bf16 v[76:79], v[76:79], v[56:59], 0
	v_max3_f32 v157, v108, s30, v109
	v_max3_f32 v157, v157, v110, v111
	v_pk_add_f32 v[160:161], v[160:161], v[176:177] op_sel_hi:[1,0]
	v_pk_add_f32 v[162:163], v[162:163], v[176:177] op_sel_hi:[1,0]
	v_cmp_gt_u32_e64 s[60:61], s101, v168
	v_cmp_gt_u32_e64 s[62:63], s101, v169
	v_cmp_gt_u32_e64 s[64:65], s101, v170
	v_cmp_gt_u32_e64 s[72:73], s101, v171
	s_xor_b32 s45, s45, s17
	s_lshl_b32 s45, s45, 7
	v_pk_mul_f32 v[104:105], v[104:105], v[126:127] op_sel_hi:[1,0]
	v_pk_mul_f32 v[106:107], v[106:107], v[126:127] op_sel_hi:[1,0]
	v_pk_fma_f32 v[104:105], v[164:165], v[128:129], v[104:105] op_sel:[0,1,0] op_sel_hi:[1,1,1] neg_lo:[0,1,0] neg_hi:[0,1,0]
	v_pk_fma_f32 v[106:107], v[166:167], v[128:129], v[106:107] op_sel:[0,1,0] op_sel_hi:[1,1,1] neg_lo:[0,1,0] neg_hi:[0,1,0]
	v_mfma_f32_16x16x32_bf16 v[100:103], v[72:75], v[60:63], v[76:79]
	v_cndmask_b32_e64 v104, v144, v104, s[74:75]
	v_cndmask_b32_e64 v105, v144, v105, s[92:93]
	v_cndmask_b32_e64 v106, v144, v106, s[94:95]
	v_cndmask_b32_e64 v107, v144, v107, s[98:99]
	v_mfma_f32_16x16x32_bf16 v[68:71], v[68:71], v[56:59], 0
	v_max3_f32 v157, v157, v104, v105
	v_max3_f32 v157, v157, v106, v107
	v_pk_add_f32 v[164:165], v[164:165], v[176:177] op_sel_hi:[1,0]
	v_pk_add_f32 v[166:167], v[166:167], v[176:177] op_sel_hi:[1,0]
	v_cmp_gt_u32_e64 s[74:75], s101, v172
	v_cmp_gt_u32_e64 s[92:93], s101, v173
	v_cmp_gt_u32_e64 s[94:95], s101, v174
	v_cmp_gt_u32_e64 s[98:99], s101, v175
	s_and_b32 s45, s45, 0x80
	s_and_b32 s50, s43, 0x60
	v_pk_mul_f32 v[100:101], v[100:101], v[126:127] op_sel_hi:[1,0]
	v_pk_mul_f32 v[102:103], v[102:103], v[126:127] op_sel_hi:[1,0]
	v_pk_fma_f32 v[100:101], v[168:169], v[128:129], v[100:101] op_sel:[0,1,0] op_sel_hi:[1,1,1] neg_lo:[0,1,0] neg_hi:[0,1,0]
	v_pk_fma_f32 v[102:103], v[170:171], v[128:129], v[102:103] op_sel:[0,1,0] op_sel_hi:[1,1,1] neg_lo:[0,1,0] neg_hi:[0,1,0]
	v_mfma_f32_16x16x32_bf16 v[200:203], v[64:67], v[60:63], v[68:71]
	v_cndmask_b32_e64 v100, v144, v100, s[60:61]
	v_cndmask_b32_e64 v101, v144, v101, s[62:63]
	v_cndmask_b32_e64 v102, v144, v102, s[64:65]
	v_cndmask_b32_e64 v103, v144, v103, s[72:73]
	v_max3_f32 v157, v157, v100, v101
	v_max3_f32 v157, v157, v102, v103
	v_pk_add_f32 v[168:169], v[168:169], v[176:177] op_sel_hi:[1,0]
	v_pk_add_f32 v[170:171], v[170:171], v[176:177] op_sel_hi:[1,0]
	s_or_b32 s45, s45, s50
	s_lshr_b32 s50, s44, 2
	s_xor_b32 s50, s50, s17
	v_bitop3_b32 v158, s45, v123, v143 bitop3:0xde
	v_bitop3_b32 v159, s45, v130, v143 bitop3:0xde
	v_pk_mul_f32 v[200:201], v[200:201], v[126:127] op_sel_hi:[1,0]
	v_pk_mul_f32 v[202:203], v[202:203], v[126:127] op_sel_hi:[1,0]
	v_pk_fma_f32 v[200:201], v[172:173], v[128:129], v[200:201] op_sel:[0,1,0] op_sel_hi:[1,1,1] neg_lo:[0,1,0] neg_hi:[0,1,0]
	v_pk_fma_f32 v[202:203], v[174:175], v[128:129], v[202:203] op_sel:[0,1,0] op_sel_hi:[1,1,1] neg_lo:[0,1,0] neg_hi:[0,1,0]
	v_cndmask_b32_e64 v200, v144, v200, s[74:75]
	v_cndmask_b32_e64 v201, v144, v201, s[92:93]
	v_cndmask_b32_e64 v202, v144, v202, s[94:95]
	v_cndmask_b32_e64 v203, v144, v203, s[98:99]
	v_max3_f32 v157, v157, v200, v201
	v_max3_f32 v157, v157, v202, v203
	v_pk_add_f32 v[172:173], v[172:173], v[176:177] op_sel_hi:[1,0]
	v_pk_add_f32 v[174:175], v[174:175], v[176:177] op_sel_hi:[1,0]
	ds_bpermute_b32 v156, v150, v157
	s_lshl_b32 s50, s50, 7
	v_mad_u32_u24 v76, v158, s18, 0
	v_mad_u32_u24 v78, v159, s18, 0
	s_and_b32 s50, s50, 0x80
	s_and_b32 s44, s52, 0x60
	s_or_b32 s44, s50, s44
	v_add_u32_e32 v72, v76, v125
	v_add_u32_e32 v74, v78, v125
	v_add_u32_e32 v76, v76, v131
	v_add_u32_e32 v78, v78, v131
	s_waitcnt lgkmcnt(0)
	v_max_f32_e32 v156, v156, v156
	v_max_f32_e32 v157, v157, v156
	ds_bpermute_b32 v156, v151, v157
	v_bitop3_b32 v158, s44, v123, v143 bitop3:0xde
	v_bitop3_b32 v159, s44, v130, v143 bitop3:0xde
	v_mad_u32_u24 v92, v158, s18, 0
	v_mad_u32_u24 v94, v159, s18, 0
	v_add_u32_e32 v88, v92, v125
	v_add_u32_e32 v90, v94, v125
	v_add_u32_e32 v92, v92, v131
	v_add_u32_e32 v94, v94, v131
	s_waitcnt lgkmcnt(0)
	v_max3_f32 v96, v154, v157, v156
	ds_read_b64_tr_b16 v[70:71], v74 offset:55296
	ds_read_b64_tr_b16 v[66:67], v74 offset:55328
	ds_read_b64_tr_b16 v[68:69], v72 offset:55296
	ds_read_b64_tr_b16 v[64:65], v72 offset:55328
	ds_read_b64_tr_b16 v[72:73], v72 offset:55360
	ds_read_b64_tr_b16 v[74:75], v74 offset:55360
	ds_read_b64_tr_b16 v[76:77], v76 offset:55296
	ds_read_b64_tr_b16 v[78:79], v78 offset:55296
	v_sub_f32_e32 v155, v154, v96
	v_pk_add_f32 v[108:109], v[108:109], v[96:97] op_sel_hi:[1,0] neg_lo:[0,1] neg_hi:[0,1]
	v_pk_add_f32 v[110:111], v[110:111], v[96:97] op_sel_hi:[1,0] neg_lo:[0,1] neg_hi:[0,1]
	v_exp_f32_e32 v154, v155
	v_pk_add_f32 v[104:105], v[104:105], v[96:97] op_sel_hi:[1,0] neg_lo:[0,1] neg_hi:[0,1]
	v_exp_f32_e32 v108, v108
	v_pk_add_f32 v[106:107], v[106:107], v[96:97] op_sel_hi:[1,0] neg_lo:[0,1] neg_hi:[0,1]
	v_exp_f32_e32 v109, v109
	v_pk_add_f32 v[100:101], v[100:101], v[96:97] op_sel_hi:[1,0] neg_lo:[0,1] neg_hi:[0,1]
	ds_read_b64_tr_b16 v[86:87], v90 offset:55296
	ds_read_b64_tr_b16 v[82:83], v90 offset:55328
	v_exp_f32_e32 v110, v110
	v_pk_add_f32 v[102:103], v[102:103], v[96:97] op_sel_hi:[1,0] neg_lo:[0,1] neg_hi:[0,1]
	ds_read_b64_tr_b16 v[84:85], v88 offset:55296
	ds_read_b64_tr_b16 v[80:81], v88 offset:55328
	v_exp_f32_e32 v111, v111
	v_pk_add_f32 v[200:201], v[200:201], v[96:97] op_sel_hi:[1,0] neg_lo:[0,1] neg_hi:[0,1]
	ds_read_b64_tr_b16 v[88:89], v88 offset:55360
	ds_read_b64_tr_b16 v[90:91], v90 offset:55360
	v_exp_f32_e32 v104, v104
	v_pk_add_f32 v[202:203], v[202:203], v[96:97] op_sel_hi:[1,0] neg_lo:[0,1] neg_hi:[0,1]
	ds_read_b64_tr_b16 v[92:93], v92 offset:55296
	ds_read_b64_tr_b16 v[94:95], v94 offset:55296
	v_exp_f32_e32 v105, v105
	v_pk_mul_f32 v[54:55], v[54:55], v[154:155] op_sel_hi:[1,0]
	v_exp_f32_e32 v106, v106
	v_pk_mul_f32 v[52:53], v[52:53], v[154:155] op_sel_hi:[1,0]
	v_exp_f32_e32 v107, v107
	v_cvt_pk_bf16_f32 v212, v108, v109
	s_add_i32 s50, s51, 2
	s_min_i32 s44, s50, s42
	s_add_i32 s45, s51, 3
	s_lshr_b32 s51, s44, 2
	s_xor_b32 s51, s51, s17
	v_exp_f32_e32 v100, v100
	v_cvt_pk_bf16_f32 v213, v110, v111
	v_exp_f32_e32 v101, v101
	v_pk_mul_f32 v[50:51], v[50:51], v[154:155] op_sel_hi:[1,0]
	v_exp_f32_e32 v102, v102
	v_pk_mul_f32 v[48:49], v[48:49], v[154:155] op_sel_hi:[1,0]
	v_exp_f32_e32 v103, v103
	v_cvt_pk_bf16_f32 v214, v104, v105
	v_exp_f32_e32 v200, v200
	v_cvt_pk_bf16_f32 v215, v106, v107
	v_exp_f32_e32 v201, v201
	v_pk_mul_f32 v[46:47], v[46:47], v[154:155] op_sel_hi:[1,0]
	v_exp_f32_e32 v202, v202
	v_pk_mul_f32 v[44:45], v[44:45], v[154:155] op_sel_hi:[1,0]
	v_exp_f32_e32 v203, v203
	v_pk_mul_f32 v[42:43], v[42:43], v[154:155] op_sel_hi:[1,0]
	v_pk_mul_f32 v[40:41], v[40:41], v[154:155] op_sel_hi:[1,0]
	s_lshl_b32 s51, s51, 7
	s_lshl_b32 s44, s44, 5
	s_waitcnt lgkmcnt(13)
	v_mfma_f32_16x16x32_bf16 v[52:55], v[68:71], v[212:215], v[52:55]
	s_min_i32 s45, s45, s42
	s_and_b32 s51, s51, 0x80
	s_and_b32 s44, s44, 0x60
	s_waitcnt lgkmcnt(12)
	v_mfma_f32_16x16x32_bf16 v[48:51], v[64:67], v[212:215], v[48:51]
	s_or_b32 s44, s51, s44
	s_lshr_b32 s51, s45, 2
	s_waitcnt lgkmcnt(10)
	v_mfma_f32_16x16x32_bf16 v[44:47], v[72:75], v[212:215], v[44:47]
	v_pk_add_f32 v[204:205], v[108:109], v[110:111]
	v_pk_add_f32 v[206:207], v[104:105], v[106:107]
	s_xor_b32 s51, s51, s17
	s_waitcnt lgkmcnt(8)
	v_mfma_f32_16x16x32_bf16 v[40:43], v[76:79], v[212:215], v[40:43]
	v_cvt_pk_bf16_f32 v216, v100, v101
	v_cvt_pk_bf16_f32 v217, v102, v103
	v_cvt_pk_bf16_f32 v218, v200, v201
	v_cvt_pk_bf16_f32 v219, v202, v203
	v_pk_add_f32 v[210:211], v[100:101], v[102:103]
	v_pk_add_f32 v[156:157], v[200:201], v[202:203]
	s_lshl_b32 s51, s51, 7
	s_lshl_b32 s45, s45, 5
	s_waitcnt lgkmcnt(5)
	v_mfma_f32_16x16x32_bf16 v[52:55], v[84:87], v[216:219], v[52:55]
	v_pk_add_f32 v[204:205], v[204:205], v[206:207]
	v_pk_add_f32 v[210:211], v[210:211], v[156:157]
	s_and_b32 s51, s51, 0x80
	s_and_b32 s45, s45, 0x60
	s_waitcnt lgkmcnt(4)
	v_mfma_f32_16x16x32_bf16 v[48:51], v[80:83], v[216:219], v[48:51]
	v_pk_add_f32 v[204:205], v[204:205], v[210:211]
	s_or_b32 s45, s51, s45
	s_add_i32 s43, s43, 64
	s_waitcnt lgkmcnt(2)
	v_mfma_f32_16x16x32_bf16 v[44:47], v[88:91], v[216:219], v[44:47]
	v_add_f32_e32 v204, v204, v205
	v_subrev_u32_e32 v152, 64, v152
	s_cmp_gt_i32 s50, s42
	s_waitcnt lgkmcnt(0)
	v_mfma_f32_16x16x32_bf16 v[40:43], v[92:95], v[216:219], v[40:43]
	v_fma_f32 v97, v97, v154, v204
	s_mov_b32 s51, s50
	s_cbranch_scc0 .LBB0_413
	s_mov_b64 s[2:3], 0
